# skip the L2 writeback at the two grid barriers whose consumers are XCD-local (guarded by a runtime XCC-mapping check)
# baseline (speedup 1.0000x reference)
.LBB0_882:
	s_waitcnt vmcnt(0)
	s_barrier
	s_mov_b64 s[4:5], exec
	v_readlane_b32 s2, v250, 4
	v_readlane_b32 s3, v250, 5
	s_and_b64 s[2:3], s[4:5], s[2:3]
	s_mov_b64 exec, s[2:3]
	s_cbranch_execz .LBB0_906
	s_add_i32 s2, 0, 0x22fc0
	v_mov_b32_e32 v0, s2
	s_waitcnt vmcnt(0) expcnt(0) lgkmcnt(0)
	buffer_inv sc1
	v_readlane_b32 s98, v250, 3
	s_and_b32 s99, s33, 7
	s_cmp_eq_u32 s98, s99
	s_cbranch_scc1 .Lxcc_ok
	v_readlane_b32 s98, v250, 1
	v_readlane_b32 s99, v250, 2
	v_mov_b32_e32 v251, 0x3200
	s_nop 4
	global_store_dword v251, v251, s[98:99] sc0 sc1
	s_waitcnt vmcnt(0)
.Lxcc_ok:
	ds_read_b32 v1, v0
	s_add_i32 s2, 0, 0x22fc4
	v_mov_b32_e32 v0, s2
	ds_read_b32 v0, v0
	s_waitcnt lgkmcnt(1)
	v_cmp_ne_u32_e32 vcc, 0, v1
	s_cbranch_vccnz .LBB0_898
	s_add_u32 s6, s68, 0x14200
	s_addc_u32 s7, s69, 0
	s_add_u32 s8, s68, 0x14400
	s_addc_u32 s9, s69, 0
	s_add_u32 s10, s68, 0x14500
	s_addc_u32 s11, s69, 0
	s_add_u32 s18, s68, 0x14600
	s_addc_u32 s19, s69, 0
	s_add_u32 s20, s68, 0x14700
	s_addc_u32 s21, s69, 0
	s_add_u32 s54, s68, 0x14800
	s_addc_u32 s55, s69, 0
	s_add_u32 s56, s68, 0x14900
	s_addc_u32 s57, s69, 0
	s_add_u32 s58, s68, 0x14a00
	s_addc_u32 s59, s69, 0
	s_add_u32 s62, s68, 0x14b00
	s_addc_u32 s63, s69, 0
	s_add_u32 s66, s68, 0x14c00
	s_addc_u32 s67, s69, 0
	s_add_u32 s82, s68, 0x14d00
	s_addc_u32 s83, s69, 0
	s_add_u32 s84, s68, 0x14e00
	s_addc_u32 s85, s69, 0
	s_add_u32 s86, s68, 0x14f00
	s_addc_u32 s87, s69, 0
	s_add_u32 s88, s68, 0x15000
	s_addc_u32 s89, s69, 0
	s_add_u32 s72, s68, 0x15100
	s_addc_u32 s73, s69, 0
	s_add_u32 s90, s68, 0x15200
	v_readlane_b32 s2, v250, 0
	s_addc_u32 s91, s69, 0
	s_mul_i32 s2, s39, s2
	s_add_u32 s12, s68, 0x15300
	s_mul_i32 s2, s2, s38
	s_addc_u32 s13, s69, 0
	s_mov_b32 s3, 1
	v_mov_b32_e32 v16, 0
	s_branch .LBB0_886

.LBB0_973:
	s_waitcnt vmcnt(0)
	s_barrier
	s_mov_b64 s[0:1], exec
	v_readlane_b32 s2, v250, 4
	v_readlane_b32 s3, v250, 5
	s_and_b64 s[2:3], s[0:1], s[2:3]
	s_mov_b64 exec, s[2:3]
	s_cbranch_execz .LBB0_997
	s_add_i32 s2, 0, 0x22fc0
	v_mov_b32_e32 v0, s2
	s_waitcnt vmcnt(0) expcnt(0) lgkmcnt(0)
	buffer_inv sc1
	v_readlane_b32 s98, v250, 1
	v_readlane_b32 s99, v250, 2
	v_mov_b32_e32 v251, 0x3200
	s_nop 4
	global_load_dword v251, v251, s[98:99] sc1
	ds_read_b32 v1, v0
	s_add_i32 s2, 0, 0x22fc4
	v_mov_b32_e32 v0, s2
	ds_read_b32 v0, v0
	s_waitcnt lgkmcnt(1)
	v_cmp_ne_u32_e32 vcc, 0, v1
	s_cbranch_vccnz .LBB0_989
	s_add_u32 s4, s68, 0x14200
	s_addc_u32 s5, s69, 0
	s_add_u32 s8, s68, 0x14400
	s_addc_u32 s9, s69, 0
	s_add_u32 s10, s68, 0x14500
	s_addc_u32 s11, s69, 0
	s_add_u32 s16, s68, 0x14600
	s_addc_u32 s17, s69, 0
	s_add_u32 s18, s68, 0x14700
	s_addc_u32 s19, s69, 0
	s_add_u32 s20, s68, 0x14800
	s_addc_u32 s21, s69, 0
	s_add_u32 s22, s68, 0x14900
	s_addc_u32 s23, s69, 0
	s_add_u32 s24, s68, 0x14a00
	s_addc_u32 s25, s69, 0
	s_add_u32 s26, s68, 0x14b00
	s_addc_u32 s27, s69, 0
	s_add_u32 s28, s68, 0x14c00
	s_addc_u32 s29, s69, 0
	s_add_u32 s44, s68, 0x14d00
	s_addc_u32 s45, s69, 0
	s_add_u32 s48, s68, 0x14e00
	s_addc_u32 s49, s69, 0
	s_add_u32 s52, s68, 0x14f00
	s_addc_u32 s53, s69, 0
	s_add_u32 s54, s68, 0x15000
	s_addc_u32 s55, s69, 0
	s_add_u32 s56, s68, 0x15100
	s_addc_u32 s57, s69, 0
	s_add_u32 s58, s68, 0x15200
	v_readlane_b32 s2, v250, 0
	s_addc_u32 s59, s69, 0
	s_mul_i32 s2, s39, s2
	s_add_u32 s12, s68, 0x15300
	s_mul_i32 s2, s2, s38
	s_addc_u32 s13, s69, 0
	s_mov_b32 s3, 1
	v_mov_b32_e32 v16, 0
	s_branch .LBB0_977

.LBB0_991:
	s_or_b64 exec, exec, s[4:5]
	v_cvt_f32_u32_e32 v4, v1
	s_waitcnt vmcnt(0)
	v_readfirstlane_b32 s2, v3
	s_add_i32 s3, 0, 0x22fc8
	v_rcp_iflag_f32_e32 v4, v4
	v_add_u32_e32 v2, s2, v2
	v_mul_f32_e32 v3, 0x4f7ffffe, v4
	v_cvt_u32_f32_e32 v3, v3
	v_sub_u32_e32 v4, 0, v1
	v_mul_lo_u32 v4, v4, v3
	v_mul_hi_u32 v4, v3, v4
	v_add_u32_e32 v3, v3, v4
	v_mul_hi_u32 v3, v2, v3
	v_mul_lo_u32 v4, v3, v1
	v_sub_u32_e32 v4, v2, v4
	v_add_u32_e32 v5, 1, v3
	v_cmp_ge_u32_e32 vcc, v4, v1
	v_add_u32_e32 v2, 1, v2
	s_nop 0
	v_cndmask_b32_e32 v3, v3, v5, vcc
	v_sub_u32_e32 v5, v4, v1
	v_cndmask_b32_e32 v4, v4, v5, vcc
	v_add_u32_e32 v5, 1, v3
	v_cmp_ge_u32_e32 vcc, v4, v1
	v_mov_b32_e32 v4, s3
	s_nop 0
	v_cndmask_b32_e32 v3, v3, v5, vcc
	ds_write_b32 v4, v3
	v_mul_lo_u32 v3, v1, v3
	v_add_u32_e32 v1, v3, v1
	v_cmp_eq_u32_e32 vcc, v2, v1
	s_and_b64 exec, exec, vcc
	s_cbranch_execz .LBB0_997
	s_mov_b64 s[4:5], exec
	v_cmp_eq_u32_e32 vcc, 0, v251
	s_cbranch_vccnz .Lnowb_a
	buffer_wbl2 sc1
.Lnowb_a:
	s_waitcnt lgkmcnt(0)
	s_waitcnt vmcnt(0)
	v_mbcnt_lo_u32_b32 v1, s4, 0
	v_mbcnt_hi_u32_b32 v1, s5, v1
	v_cmp_eq_u32_e32 vcc, 0, v1
	s_and_saveexec_b64 s[8:9], vcc
	s_cbranch_execz .LBB0_994
	s_bcnt1_i32_b64 s2, s[4:5]
	v_mov_b32_e32 v2, 0x17000
	v_mov_b32_e32 v3, s2
	global_atomic_add v2, v2, v3, s[68:69] offset:1024 sc0

.LBB0_1129:
	s_cmp_gt_i32 s95, 11
	s_cselect_b64 s[0:1], -1, 0
	s_and_b64 s[2:3], s[4:5], s[0:1]
	s_andn2_b64 vcc, exec, s[2:3]
	s_cbranch_vccnz .LBB0_1181
	s_waitcnt vmcnt(0)
	s_barrier
	s_mov_b64 s[4:5], exec
	v_readlane_b32 s2, v250, 4
	v_readlane_b32 s3, v250, 5
	s_and_b64 s[2:3], s[4:5], s[2:3]
	s_mov_b64 exec, s[2:3]
	s_cbranch_execz .LBB0_1180
	s_add_i32 s2, 0, 0x22fc0
	v_mov_b32_e32 v0, s2
	s_waitcnt vmcnt(0) expcnt(0) lgkmcnt(0)
	buffer_inv sc1
	v_readlane_b32 s98, v250, 1
	v_readlane_b32 s99, v250, 2
	v_mov_b32_e32 v251, 0x3200
	s_nop 4
	global_load_dword v251, v251, s[98:99] sc1
	ds_read_b32 v2, v0
	s_add_i32 s2, 0, 0x22fc4
	v_mov_b32_e32 v0, s2
	ds_read_b32 v0, v0
	s_waitcnt lgkmcnt(1)
	v_cmp_ne_u32_e32 vcc, 0, v2
	s_cbranch_vccnz .LBB0_1146
	s_add_u32 s8, s68, 0x14200
	s_addc_u32 s9, s69, 0
	s_add_u32 s10, s68, 0x14400
	s_addc_u32 s11, s69, 0
	s_add_u32 s12, s68, 0x14500
	s_addc_u32 s13, s69, 0
	s_add_u32 s14, s68, 0x14600
	s_addc_u32 s15, s69, 0
	s_add_u32 s16, s68, 0x14700
	s_addc_u32 s17, s69, 0
	s_add_u32 s18, s68, 0x14800
	s_addc_u32 s19, s69, 0
	s_add_u32 s20, s68, 0x14900
	s_addc_u32 s21, s69, 0
	s_add_u32 s22, s68, 0x14a00
	s_addc_u32 s23, s69, 0
	s_add_u32 s24, s68, 0x14b00
	s_addc_u32 s25, s69, 0
	s_add_u32 s26, s68, 0x14c00
	s_addc_u32 s27, s69, 0
	s_add_u32 s28, s68, 0x14d00
	s_addc_u32 s29, s69, 0
	s_add_u32 s36, s68, 0x14e00
	s_addc_u32 s37, s69, 0
	s_add_u32 s40, s68, 0x14f00
	s_addc_u32 s41, s69, 0
	s_add_u32 s42, s68, 0x15000
	s_addc_u32 s43, s69, 0
	s_add_u32 s44, s68, 0x15100
	s_addc_u32 s45, s69, 0
	s_add_u32 s46, s68, 0x15200
	v_readlane_b32 s2, v250, 0
	s_addc_u32 s47, s69, 0
	s_mul_i32 s2, s39, s2
	s_add_u32 s48, s68, 0x15300
	s_mul_i32 s2, s2, s38
	s_addc_u32 s49, s69, 0
	s_mov_b32 s3, 1
	v_mov_b32_e32 v16, 0
	s_branch .LBB0_1134

.LBB0_1162:
	s_andn2_saveexec_b64 s[2:3], s[8:9]
	s_cbranch_execz .LBB0_1180
	s_mov_b64 s[8:9], exec
	v_cmp_eq_u32_e32 vcc, 0, v251
	s_cbranch_vccnz .Lnowb_b
	buffer_wbl2 sc1
.Lnowb_b:
	s_waitcnt lgkmcnt(0)
	s_waitcnt vmcnt(0)
	v_mbcnt_lo_u32_b32 v1, s8, 0
	v_mbcnt_hi_u32_b32 v1, s9, v1
	v_cmp_eq_u32_e32 vcc, 0, v1
	s_and_saveexec_b64 s[10:11], vcc
	s_cbranch_execz .LBB0_1165
	s_bcnt1_i32_b64 s2, s[8:9]
	v_mov_b32_e32 v2, 0x17000
	v_mov_b32_e32 v3, s2
	global_atomic_add v2, v2, v3, s[68:69] offset:1024 sc0

	.amdhsa_kernel _Z8mega_fwd4Args
		.amdhsa_group_segment_fixed_size 0
		.amdhsa_private_segment_fixed_size 0
		.amdhsa_kernarg_size 464
		.amdhsa_user_sgpr_count 2
		.amdhsa_user_sgpr_dispatch_ptr 0
		.amdhsa_user_sgpr_queue_ptr 0
		.amdhsa_user_sgpr_kernarg_segment_ptr 1
		.amdhsa_user_sgpr_dispatch_id 0
		.amdhsa_user_sgpr_kernarg_preload_length 0
		.amdhsa_user_sgpr_kernarg_preload_offset 0
		.amdhsa_user_sgpr_private_segment_size 0
		.amdhsa_uses_dynamic_stack 0
		.amdhsa_enable_private_segment 0
		.amdhsa_system_sgpr_workgroup_id_x 1
		.amdhsa_system_sgpr_workgroup_id_y 0
		.amdhsa_system_sgpr_workgroup_id_z 0
		.amdhsa_system_sgpr_workgroup_info 0
		.amdhsa_system_vgpr_workitem_id 2
		.amdhsa_next_free_vgpr 252
		.amdhsa_next_free_sgpr 102
		.amdhsa_accum_offset 252
		.amdhsa_reserve_vcc 1
		.amdhsa_float_round_mode_32 0
		.amdhsa_float_round_mode_16_64 0
		.amdhsa_float_denorm_mode_32 3
		.amdhsa_float_denorm_mode_16_64 3
		.amdhsa_dx10_clamp 1
		.amdhsa_ieee_mode 1
		.amdhsa_fp16_overflow 0
		.amdhsa_tg_split 0
		.amdhsa_exception_fp_ieee_invalid_op 0
		.amdhsa_exception_fp_denorm_src 0
		.amdhsa_exception_fp_ieee_div_zero 0
		.amdhsa_exception_fp_ieee_overflow 0
		.amdhsa_exception_fp_ieee_underflow 0
		.amdhsa_exception_fp_ieee_inexact 0
		.amdhsa_exception_int_div_zero 0
	.end_amdhsa_kernel

amdhsa.kernels:
  - .agpr_count:     0
    .args:
      - .offset:         0
        .size:           208
        .value_kind:     by_value
      - .offset:         208
        .size:           4
        .value_kind:     hidden_block_count_x
      - .offset:         212
        .size:           4
        .value_kind:     hidden_block_count_y
      - .offset:         216
        .size:           4
        .value_kind:     hidden_block_count_z
      - .offset:         220
        .size:           2
        .value_kind:     hidden_group_size_x
      - .offset:         222
        .size:           2
        .value_kind:     hidden_group_size_y
      - .offset:         224
        .size:           2
        .value_kind:     hidden_group_size_z
      - .offset:         226
        .size:           2
        .value_kind:     hidden_remainder_x
      - .offset:         228
        .size:           2
        .value_kind:     hidden_remainder_y
      - .offset:         230
        .size:           2
        .value_kind:     hidden_remainder_z
      - .offset:         248
        .size:           8
        .value_kind:     hidden_global_offset_x
      - .offset:         256
        .size:           8
        .value_kind:     hidden_global_offset_y
      - .offset:         264
        .size:           8
        .value_kind:     hidden_global_offset_z
      - .offset:         272
        .size:           2
        .value_kind:     hidden_grid_dims
      - .offset:         296
        .size:           8
        .value_kind:     hidden_multigrid_sync_arg
      - .offset:         328
        .size:           4
        .value_kind:     hidden_dynamic_lds_size
    .group_segment_fixed_size: 0
    .kernarg_segment_align: 8
    .kernarg_segment_size: 464
    .language:       OpenCL C
    .language_version:
      - 2
      - 0
    .max_flat_workgroup_size: 512
    .name:           _Z8mega_fwd4Args
    .private_segment_fixed_size: 0
    .sgpr_count:     108
    .sgpr_spill_count: 65
    .symbol:         _Z8mega_fwd4Args.kd
    .uniform_work_group_size: 1
    .uses_dynamic_stack: false
    .vgpr_count:     252
    .vgpr_spill_count: 0
    .wavefront_size: 64
